# prep phase token-shift/lora loop: next iteration's row loads issued one iteration ahead, loop-invariant mix-parameter loads hoisted
# baseline (speedup 1.0000x reference)
.LBB0_382:
	s_or_b64 exec, exec, s[0:1]
	v_readlane_b32 s0, v247, 2
	v_readlane_b32 s6, v247, 8
	v_readlane_b32 s1, v247, 3
	s_add_u32 s18, s0, 0x1000000
	s_mov_b32 s53, 0
	s_mov_b32 s52, s6
	v_readlane_b32 s2, v247, 4
	v_readlane_b32 s3, v247, 5
	s_addc_u32 s19, s1, 0
	s_lshl_b64 s[26:27], s[52:53], 8
	s_mov_b64 s[0:1], 0x100000
	s_waitcnt lgkmcnt(0)
	s_barrier
	v_readlane_b32 s4, v247, 6
	v_readlane_b32 s5, v247, 7
	v_readlane_b32 s7, v247, 9
	v_cmp_gt_u64_e64 s[2:3], s[0:1], v[134:135]
	s_mov_b64 s[0:1], exec
	s_nop 0
	v_writelane_b32 v246, s2, 28
	s_nop 1
	v_writelane_b32 v246, s3, 29
	s_and_b64 s[2:3], s[0:1], s[2:3]
	s_mov_b64 exec, s[2:3]
	s_cbranch_execz .LBB0_411
	v_readlane_b32 s36, v247, 13
	v_readlane_b32 s48, v247, 25
	v_readlane_b32 s49, v247, 26
	v_readlane_b32 s50, v247, 27
	v_readlane_b32 s51, v247, 28
	s_mov_b64 s[20:21], s[48:49]
	v_readlane_b32 s4, v247, 0
	s_add_u32 s2, s20, 0x3000
	v_readlane_b32 s5, v247, 1
	s_addc_u32 s3, s21, 0
	s_lshl_b64 s[4:5], s[4:5], 11
	v_lshl_add_u64 v[16:17], v[130:131], 3, s[4:5]
	s_lshl_b64 s[4:5], s[52:53], 11
	s_mov_b64 s[6:7], 0
	v_mov_b32_e32 v19, 0
	v_mov_b64_e32 v[20:21], v[134:135]
	v_readlane_b32 s37, v247, 14
	v_readlane_b32 s38, v247, 15
	v_readlane_b32 s39, v247, 16
	v_readlane_b32 s40, v247, 17
	v_readlane_b32 s41, v247, 18
	v_readlane_b32 s42, v247, 19
	v_readlane_b32 s43, v247, 20
	v_readlane_b32 s44, v247, 21
	v_readlane_b32 s45, v247, 22
	v_readlane_b32 s46, v247, 23
	v_readlane_b32 s47, v247, 24
	s_mov_b64 s[22:23], s[50:51]
	v_and_b32_e32 v46, 0x7fff00, v16
	v_and_b32_e32 v47, 0xf8, v16
	v_lshlrev_b32_e32 v48, 2, v47
	v_lshlrev_b32_e32 v46, 1, v46
	v_lshl_add_u32 v46, v47, 1, v46
	v_and_b32_e32 v47, 0xffe0, v20
	v_lshlrev_b32_e32 v47, 4, v47
	v_min_u32_e32 v47, 0x200, v47
	v_sub_u32_e32 v47, v46, v47
	global_load_dwordx4 v[28:31], v46, s[68:69]
	global_load_dwordx4 v[32:35], v47, s[68:69]
	global_load_dwordx4 v[36:39], v48, s[2:3]
	global_load_dwordx4 v[40:43], v48, s[2:3] offset:16
	s_waitcnt vmcnt(0)
	s_branch .LBB0_385

.LBB0_385:
	v_and_b32_e32 v0, 0x7fff00, v16
	v_and_b32_e32 v24, 0xf8, v16
	v_lshlrev_b32_e32 v18, 1, v0
	v_lshlrev_b32_e32 v22, 1, v24
	v_mov_b32_e32 v23, v19
	v_and_b32_e32 v4, 0xffe0, v20
	v_cmp_ne_u32_e32 vcc, 0, v4
	s_waitcnt vmcnt(1)
	v_mov_b32_e32 v0, v28
	v_mov_b32_e32 v1, v29
	v_mov_b32_e32 v2, v30
	v_mov_b32_e32 v3, v31
	v_cndmask_b32_e32 v4, 0, v32, vcc
	v_cndmask_b32_e32 v5, 0, v33, vcc
	v_cndmask_b32_e32 v6, 0, v34, vcc
	v_cndmask_b32_e32 v7, 0, v35, vcc
	v_mov_b32_e32 v12, v36
	v_mov_b32_e32 v13, v37
	v_mov_b32_e32 v14, v38
	v_mov_b32_e32 v15, v39
	v_mov_b32_e32 v8, v40
	v_mov_b32_e32 v9, v41
	v_mov_b32_e32 v10, v42
	v_mov_b32_e32 v11, v43
	v_add_u32_e32 v44, s4, v16
	v_add_u32_e32 v45, s26, v20
	v_cmp_gt_u32_e32 vcc, 0x100000, v45
	s_nop 1
	v_cndmask_b32_e32 v44, v16, v44, vcc
	v_cndmask_b32_e32 v45, v20, v45, vcc
	v_and_b32_e32 v46, 0x7fff00, v44
	v_and_b32_e32 v47, 0xf8, v44
	v_lshlrev_b32_e32 v46, 1, v46
	v_lshl_add_u32 v46, v47, 1, v46
	v_and_b32_e32 v47, 0xffe0, v45
	v_lshlrev_b32_e32 v47, 4, v47
	v_min_u32_e32 v47, 0x200, v47
	v_sub_u32_e32 v47, v46, v47
	global_load_dwordx4 v[28:31], v46, s[68:69]
	global_load_dwordx4 v[32:35], v47, s[68:69]
	s_movk_i32 s8, 0x7f
	v_cmp_lt_u32_e64 s[10:11], 63, v24
	v_cmp_lt_u32_e64 s[8:9], s8, v24
	v_lshlrev_b32_e32 v24, 16, v0
	v_lshlrev_b32_e32 v26, 16, v4
	v_and_b32_e32 v25, 0xffff0000, v0
	v_and_b32_e32 v27, 0xffff0000, v4
	v_pk_add_f32 v[26:27], v[26:27], v[24:25] neg_lo:[0,1] neg_hi:[0,1]
	v_pk_fma_f32 v[12:13], v[26:27], v[12:13], v[24:25]
	s_and_saveexec_b64 s[12:13], s[10:11]
	s_xor_b64 s[12:13], exec, s[12:13]
	s_cbranch_execz .LBB0_391
	s_and_saveexec_b64 s[14:15], s[8:9]
	s_cbranch_execz .LBB0_390
	v_mul_f32_e32 v0, 0xbfb8aa3b, v12
	v_exp_f32_e32 v12, v0
	v_mul_f32_e32 v0, 0xbfb8aa3b, v13
	v_exp_f32_e32 v13, v0
	s_nop 0
	v_pk_add_f32 v[12:13], v[12:13], 1.0 op_sel_hi:[1,0]
	s_nop 0
	v_div_scale_f32 v0, s[16:17], v13, v13, 1.0
	v_rcp_f32_e32 v4, v0
	s_nop 0
	v_fma_f32 v23, -v0, v4, 1.0
	v_fmac_f32_e32 v4, v23, v4
	v_div_scale_f32 v23, vcc, 1.0, v13, 1.0
	v_mul_f32_e32 v24, v23, v4
	v_fma_f32 v25, -v0, v24, v23
	v_fmac_f32_e32 v24, v25, v4
	v_fma_f32 v0, -v0, v24, v23
	v_div_fmas_f32 v0, v0, v4, v24
	v_div_fixup_f32 v13, v0, v13, 1.0
	v_div_scale_f32 v0, s[16:17], v12, v12, 1.0
	v_rcp_f32_e32 v4, v0
	s_nop 0
	v_fma_f32 v23, -v0, v4, 1.0
	v_fmac_f32_e32 v4, v23, v4
	v_div_scale_f32 v23, vcc, 1.0, v12, 1.0
	v_mul_f32_e32 v24, v23, v4
	v_fma_f32 v25, -v0, v24, v23
	v_fmac_f32_e32 v24, v25, v4
	v_fma_f32 v0, -v0, v24, v23
	v_div_fmas_f32 v0, v0, v4, v24
	v_div_fixup_f32 v12, v0, v12, 1.0

.LBB0_399:
	s_or_b64 exec, exec, s[12:13]
	v_lshlrev_b32_e32 v4, 16, v2
	v_lshlrev_b32_e32 v14, 16, v6
	v_and_b32_e32 v5, 0xffff0000, v2
	v_and_b32_e32 v15, 0xffff0000, v6
	v_pk_add_f32 v[14:15], v[14:15], v[4:5] neg_lo:[0,1] neg_hi:[0,1]
	v_pk_fma_f32 v[4:5], v[14:15], v[8:9], v[4:5]
	s_and_saveexec_b64 s[12:13], s[10:11]
	s_xor_b64 s[12:13], exec, s[12:13]
	s_cbranch_execz .LBB0_403
	s_and_saveexec_b64 s[14:15], s[8:9]
	s_cbranch_execz .LBB0_402
	v_mul_f32_e32 v2, 0xbfb8aa3b, v4
	v_exp_f32_e32 v4, v2
	v_mul_f32_e32 v2, 0xbfb8aa3b, v5
	v_exp_f32_e32 v5, v2
	s_nop 0
	v_pk_add_f32 v[4:5], v[4:5], 1.0 op_sel_hi:[1,0]
	s_nop 0
	v_div_scale_f32 v2, s[16:17], v5, v5, 1.0
	v_rcp_f32_e32 v6, v2
	s_nop 0
	v_fma_f32 v8, -v2, v6, 1.0
	v_fmac_f32_e32 v6, v8, v6
	v_div_scale_f32 v8, vcc, 1.0, v5, 1.0
	v_mul_f32_e32 v9, v8, v6
	v_fma_f32 v14, -v2, v9, v8
	v_fmac_f32_e32 v9, v14, v6
	v_fma_f32 v2, -v2, v9, v8
	v_div_fmas_f32 v2, v2, v6, v9
	v_div_fixup_f32 v5, v2, v5, 1.0
	v_div_scale_f32 v2, s[16:17], v4, v4, 1.0
	v_rcp_f32_e32 v6, v2
	s_nop 0
	v_fma_f32 v8, -v2, v6, 1.0
	v_fmac_f32_e32 v6, v8, v6
	v_div_scale_f32 v8, vcc, 1.0, v4, 1.0
	v_mul_f32_e32 v9, v8, v6
	v_fma_f32 v14, -v2, v9, v8
	v_fmac_f32_e32 v9, v14, v6
	v_fma_f32 v2, -v2, v9, v8
	v_div_fmas_f32 v2, v2, v6, v9
	v_div_fixup_f32 v4, v2, v4, 1.0

.LBB0_411:
	s_or_b64 exec, exec, s[0:1]
	s_waitcnt vmcnt(0)
	s_mov_b64 s[0:1], 0x300000
	v_cmp_gt_u64_e32 vcc, s[0:1], v[134:135]
	s_and_saveexec_b64 s[2:3], vcc
	s_cbranch_execz .LBB0_416
	v_readlane_b32 s36, v247, 45
	v_ffbh_u32_e32 v0, 0
	v_readlane_b32 s38, v247, 47
	v_readlane_b32 s39, v247, 48
	v_readlane_b32 s40, v247, 49
	v_readlane_b32 s41, v247, 50
	v_min_u32_e32 v29, 32, v0
	s_mov_b64 s[4:5], 0
	v_mov_b32_e32 v1, 0
	v_mov_b32_e32 v24, s39
	v_mov_b32_e32 v25, s41
	v_mov_b32_e32 v26, s38
	v_mov_b32_e32 v27, s40
	v_mov_b32_e32 v28, 0x358637bd
	v_sub_u32_e32 v30, 32, v29
	v_mov_b64_e32 v[2:3], v[134:135]
	v_readlane_b32 s37, v247, 46
	v_readlane_b32 s42, v248, 18
	v_readlane_b32 s43, v248, 19
	v_readlane_b32 s44, v247, 53
	v_readlane_b32 s45, v247, 54
	v_readlane_b32 s46, v247, 55
	v_readlane_b32 s47, v247, 56
	v_readlane_b32 s48, v247, 57
	v_readlane_b32 s49, v247, 58
	v_readlane_b32 s50, v247, 59
	v_readlane_b32 s51, v247, 60
	s_mov_b32 s0, 0xaaaaaaab
	v_mul_hi_u32 v90, v2, s0
	v_lshrrev_b32_e32 v90, 6, v90
	s_movk_i32 s0, 0x60
	v_mul_lo_u32 v91, v90, s0
	v_sub_u32_e32 v91, v2, v91
	v_ashrrev_i32_e32 v92, 2, v91
	v_and_b32_e32 v93, 3, v91
	v_mul_hi_i32_i24_e32 v95, 0x1200, v90
	v_mul_i32_i24_e32 v94, 0x1200, v90
	v_lshlrev_b32_e32 v96, 6, v92
	v_lshl_add_u64 v[94:95], s[70:71], 0, v[94:95]
	v_ashrrev_i32_e32 v97, 31, v96
	v_lshl_add_u64 v[94:95], v[96:97], 1, v[94:95]
	v_lshlrev_b32_e32 v96, 5, v93
	v_mov_b32_e32 v97, 0
	v_lshl_add_u64 v[94:95], v[94:95], 0, v[96:97]
	global_load_dwordx4 v[80:83], v[94:95], off
	global_load_dwordx4 v[84:87], v[94:95], off offset:16
	s_waitcnt vmcnt(0)
	s_branch .LBB0_414
